# hyena MFMA loops: out-of-range z fragments read from an LDS zero block (address select) instead of per-read exec masking
# baseline (speedup 1.0000x reference)
; #define LAS __attribute__((address_space(3)))
; __device__ __forceinline__ v4u pack8(const float (&f)[8]) { v4u o; o.x = pk2(f[0], f[1]); o.y = pk2(f[2], f[3]); o.z = pk2(f[4], f[5]); o.w = pk2(f[6], f[7]); return o; }
; __device__ __forceinline__ void phase_hyena(int l, LAS unsigned char* lds, int G) {
;     ...
; #pragma unroll
;             for (int b = 0; b < 8; ++b) { const bf16r* xr = X1T + ((size_t)c * BATCH + b) * SEQ + tid * 8; const bf16r* vr = VT + ((size_t)c * BATCH + b) * SEQ + tid * 8;
;                 float xf[10], vf[10]; { float t8[8]; unpack8(*(const v4u*)xr, t8);
; #pragma unroll
;                     for (int e = 0; e < 8; ++e) xf[e + 1] = t8[e]; unpack8(*(const v4u*)vr, t8);
; #pragma unroll
;                     for (int e = 0; e < 8; ++e) vf[e + 1] = t8[e]; }
;                 xf[0] = tid > 0 ? bf1(xr[-1]) : 0.f; vf[0] = tid > 0 ? bf1(vr[-1]) : 0.f; xf[9] = tid < NTHR - 1 ? bf1(xr[8]) : 0.f; vf[9] = tid < NTHR - 1 ? bf1(vr[8]) : 0.f;
;                 float z[8];
; #pragma unroll
;                 for (int e = 0; e < 8; ++e) z[e] = (wx0 * xf[e] + wx1 * xf[e + 1] + wx2 * xf[e + 2] + bx) * (wv0 * vf[e] + wv1 * vf[e + 1] + wv2 * vf[e + 2] + bv);
;                 *(LAS v4u*)(Zs + b * ZPITCH + tid * 16) = pack8(z); }
;         }
; #pragma unroll
;         for (int i = 0; i < 2; ++i) { *(LAS v4u*)((LAS unsigned char*)rl + (i * NTHR + tid) * 16) = *(const v4u*)(RG + (size_t)c * 8192 + (i * NTHR + tid) * 8);
;             *(LAS v4u*)((LAS unsigned char*)rl + RG1_LDS + (i * NTHR + tid) * 16) = *(const v4u*)(RG1 + (size_t)c * 8192 + (i * NTHR + tid) * 8); }
;         __syncthreads();
;         const float invn = 1.0f / NORM[c], bias = hb[c];
;         f32x16 acc[2][2];
; #pragma unroll
;         for (int a = 0; a < 2; ++a)
; #pragma unroll
;             for (int bb = 0; bb < 2; ++bb) acc[a][bb] = f32x16{};
;         const int Dlo = (8 * wave - 63) > -63 ? (8 * wave - 63) : -63, Dhi = (8 * wave + 7) < 63 ? (8 * wave + 7) : 63;
;         const LAS unsigned char* zb = Zs + (r32 & 7) * ZPITCH + hi * 16;
.LBB0_508:
	s_or_b64 exec, exec, s[48:49]
	s_waitcnt vmcnt(1)
	v_and_b32_e32 v35, 0xffff0000, v2
	v_lshlrev_b32_e32 v37, 16, v3
	v_and_b32_e32 v47, 0xffff0000, v3
	s_waitcnt vmcnt(0)
	v_and_b32_e32 v3, 0xffff0000, v6
	v_lshlrev_b32_e32 v53, 16, v7
	v_and_b32_e32 v7, 0xffff0000, v7
	v_mov_b32_e32 v36, v35
	v_mov_b32_e32 v52, v3
	v_mov_b32_e32 v41, v7
	v_lshlrev_b32_e32 v34, 16, v2
	v_mov_b32_e32 v45, v37
	v_mov_b32_e32 v46, v37
	v_lshlrev_b32_e32 v2, 16, v6
	v_mov_b32_e32 v43, v47
	v_pk_mul_f32 v[20:21], v[20:21], v[40:41]
	v_pk_mul_f32 v[36:37], v[32:33], v[36:37]
	v_pk_mul_f32 v[40:41], v[28:29], v[52:53]
	v_mov_b32_e32 v44, v34
	v_mov_b32_e32 v48, v35
	v_mov_b32_e32 v54, v2
	v_mov_b32_e32 v55, v53
	v_mov_b32_e32 v6, v53
	v_mov_b32_e32 v56, v3
	v_pk_mul_f32 v[18:19], v[18:19], v[42:43]
	v_pk_fma_f32 v[34:35], v[30:31], v[34:35], v[36:37]
	v_pk_fma_f32 v[2:3], v[26:27], v[2:3], v[40:41]
	v_lshlrev_b32_e32 v49, 16, v4
	v_lshlrev_b32_e32 v57, 16, v8
	v_pk_fma_f32 v[34:35], v[12:13], v[46:47], v[34:35]
	v_pk_fma_f32 v[2:3], v[16:17], v[6:7], v[2:3]
	v_pk_fma_f32 v[18:19], v[24:25], v[44:45], v[18:19]
	v_pk_fma_f32 v[20:21], v[22:23], v[54:55], v[20:21]
	v_pk_add_f32 v[34:35], v[14:15], v[34:35]
	v_pk_add_f32 v[2:3], v[10:11], v[2:3]
	v_pk_fma_f32 v[18:19], v[12:13], v[48:49], v[18:19]
	v_pk_fma_f32 v[20:21], v[16:17], v[56:57], v[20:21]
	v_pk_mul_f32 v[2:3], v[34:35], v[2:3]
	v_pk_add_f32 v[18:19], v[14:15], v[18:19]
	v_pk_add_f32 v[20:21], v[10:11], v[20:21]
	v_lshlrev_b32_e32 v51, 16, v5
	v_pk_mul_f32 v[18:19], v[18:19], v[20:21]
	v_and_b32_sdwa v20, v2, v220 dst_sel:DWORD dst_unused:UNUSED_PAD src0_sel:WORD_1 src1_sel:DWORD
	v_and_b32_sdwa v6, v3, v220 dst_sel:DWORD dst_unused:UNUSED_PAD src0_sel:WORD_1 src1_sel:DWORD
	v_add3_u32 v2, v2, v20, s72
	v_and_b32_sdwa v20, v18, v220 dst_sel:DWORD dst_unused:UNUSED_PAD src0_sel:WORD_1 src1_sel:DWORD
	v_and_b32_e32 v5, 0xffff0000, v5
	v_and_b32_e32 v4, 0xffff0000, v4
	v_add3_u32 v3, v3, v6, s72
	v_and_b32_e32 v2, 0xffff0000, v2
	v_and_b32_sdwa v6, v19, v220 dst_sel:DWORD dst_unused:UNUSED_PAD src0_sel:WORD_1 src1_sel:DWORD
	v_add3_u32 v18, v18, v20, s72
	v_mov_b32_e32 v20, v49
	v_mov_b32_e32 v21, v51
	v_lshlrev_b32_e32 v59, 16, v9
	v_add3_u32 v6, v19, v6, s72
	v_or_b32_sdwa v2, v18, v2 dst_sel:DWORD dst_unused:UNUSED_PAD src0_sel:WORD_1 src1_sel:DWORD
	v_pk_mov_b32 v[18:19], v[46:47], v[4:5] op_sel:[1,0]
	v_pk_mul_f32 v[20:21], v[32:33], v[20:21]
	v_and_b32_e32 v9, 0xffff0000, v9
	v_and_b32_e32 v8, 0xffff0000, v8
	v_and_b32_e32 v6, 0xffff0000, v6
	v_pk_fma_f32 v[18:19], v[30:31], v[18:19], v[20:21]
	v_mov_b32_e32 v20, v57
	v_mov_b32_e32 v21, v59
	v_or_b32_sdwa v3, v6, v3 dst_sel:DWORD dst_unused:UNUSED_PAD src0_sel:DWORD src1_sel:WORD_1
	v_pk_mov_b32 v[6:7], v[6:7], v[8:9] op_sel:[1,0]
	v_pk_mul_f32 v[20:21], v[28:29], v[20:21]
	v_pk_fma_f32 v[18:19], v[12:13], v[4:5], v[18:19]
	v_pk_fma_f32 v[6:7], v[26:27], v[6:7], v[20:21]
	v_mov_b32_e32 v48, v5
	v_pk_fma_f32 v[6:7], v[16:17], v[8:9], v[6:7]
	v_mov_b32_e32 v56, v9
	v_mov_b32_e32 v50, v4
	v_mov_b32_e32 v58, v8
	v_pk_add_f32 v[18:19], v[14:15], v[18:19]
	v_pk_add_f32 v[6:7], v[10:11], v[6:7]
	v_pk_mul_f32 v[4:5], v[24:25], v[48:49]
	v_pk_mul_f32 v[8:9], v[22:23], v[56:57]
	v_pk_mul_f32 v[6:7], v[18:19], v[6:7]
	v_pk_fma_f32 v[4:5], v[24:25], v[50:51], v[4:5] op_sel:[0,0,1] op_sel_hi:[1,1,0]
	v_pk_mov_b32 v[18:19], v[50:51], v[38:39] op_sel:[1,0]
	v_pk_fma_f32 v[8:9], v[22:23], v[58:59], v[8:9] op_sel:[0,0,1] op_sel_hi:[1,1,0]
	v_mov_b32_e32 v38, v59
	v_pk_fma_f32 v[4:5], v[12:13], v[18:19], v[4:5]
	v_pk_fma_f32 v[8:9], v[16:17], v[38:39], v[8:9]
	v_pk_add_f32 v[4:5], v[14:15], v[4:5]
	v_pk_add_f32 v[8:9], v[10:11], v[8:9]
	s_lshl_b64 s[2:3], s[34:35], 14
	v_pk_mul_f32 v[4:5], v[4:5], v[8:9]
	v_and_b32_sdwa v8, v7, v220 dst_sel:DWORD dst_unused:UNUSED_PAD src0_sel:WORD_1 src1_sel:DWORD
	v_and_b32_sdwa v9, v6, v220 dst_sel:DWORD dst_unused:UNUSED_PAD src0_sel:WORD_1 src1_sel:DWORD
	v_add3_u32 v6, v6, v9, s72
	v_add3_u32 v7, v7, v8, s72
	v_and_b32_sdwa v8, v5, v220 dst_sel:DWORD dst_unused:UNUSED_PAD src0_sel:WORD_1 src1_sel:DWORD
	v_and_b32_sdwa v9, v4, v220 dst_sel:DWORD dst_unused:UNUSED_PAD src0_sel:WORD_1 src1_sel:DWORD
	v_add3_u32 v5, v5, v8, s72
	v_add3_u32 v4, v4, v9, s72
	v_and_b32_e32 v5, 0xffff0000, v5
	v_and_b32_e32 v4, 0xffff0000, v4
	s_add_u32 s14, s62, s2
	v_or_b32_sdwa v5, v5, v7 dst_sel:DWORD dst_unused:UNUSED_PAD src0_sel:DWORD src1_sel:WORD_1
	v_or_b32_sdwa v4, v4, v6 dst_sel:DWORD dst_unused:UNUSED_PAD src0_sel:DWORD src1_sel:WORD_1
	s_addc_u32 s15, s63, s3
	ds_write_b128 v0, v[2:5] offset:57456
	v_lshl_add_u64 v[2:3], s[14:15], 0, v[136:137]
	v_mov_b64_e32 v[2:3], v[202:203]
	v_mov_b64_e32 v[4:5], v[204:205]
	s_add_u32 s2, s64, s2
	v_readlane_b32 s28, v247, 30
	s_addc_u32 s3, s65, s3
	v_readlane_b32 s29, v247, 31
	v_add_u32_e32 v0, s28, v141
	s_waitcnt vmcnt(0)
	ds_write_b128 v0, v[2:5]
	v_lshl_add_u64 v[2:3], s[2:3], 0, v[136:137]
	v_mov_b64_e32 v[2:3], v[206:207]
	v_mov_b64_e32 v[4:5], v[208:209]
	v_add_u32_e32 v0, s29, v141
	s_waitcnt vmcnt(0)
	ds_write_b128 v0, v[2:5]
	v_lshl_add_u64 v[2:3], s[14:15], 0, v[138:139]
	v_mov_b64_e32 v[2:3], v[210:211]
	v_mov_b64_e32 v[4:5], v[212:213]
	v_add_u32_e32 v0, s28, v129
	s_waitcnt vmcnt(0)
	ds_write_b128 v0, v[2:5]
	v_lshl_add_u64 v[2:3], s[2:3], 0, v[138:139]
	v_mov_b64_e32 v[2:3], v[214:215]
	v_mov_b64_e32 v[4:5], v[216:217]
	s_add_u32 s2, s66, s46
	v_add_u32_e32 v0, s29, v129
	s_addc_u32 s3, s67, s47
	s_waitcnt vmcnt(0)
	ds_write_b128 v0, v[2:5]
	v_and_b32_e32 v227, 7, v218
	v_lshlrev_b32_e32 v227, 4, v227
	v_add_u32_e32 v227, 0x19000, v227
	v_mov_b32_e32 v228, 0
	v_mov_b32_e32 v229, 0
	v_mov_b32_e32 v230, 0
	v_mov_b32_e32 v231, 0
	ds_write_b128 v227, v[228:231]
	v_mov_b32_e32 v227, 0x19000
	s_waitcnt lgkmcnt(0)
	s_barrier
	global_load_dword v154, v1, s[2:3]
	s_add_u32 s2, s68, s46
	s_addc_u32 s3, s69, s47
	global_load_dword v140, v1, s[2:3]
	s_andn2_b64 vcc, exec, s[16:17]
	s_cbranch_vccnz .LBB0_519
	v_mov_b32_e32 v16, 0
	v_mov_b32_e32 v0, v145
	v_mov_b32_e32 v14, v144
	v_mov_b32_e32 v15, v143
	s_mov_b32 s2, s70
	v_mov_b32_e32 v17, v16
	v_mov_b32_e32 v18, v16
	v_mov_b32_e32 v19, v16
	v_mov_b32_e32 v20, v16
	v_mov_b32_e32 v21, v16
	v_mov_b32_e32 v22, v16
	v_mov_b32_e32 v23, v16
	v_mov_b32_e32 v24, v16
	v_mov_b32_e32 v25, v16
	v_mov_b32_e32 v26, v16
	v_mov_b32_e32 v27, v16
	v_mov_b32_e32 v28, v16
	v_mov_b32_e32 v29, v16
	v_mov_b32_e32 v30, v16
	v_mov_b32_e32 v31, v16
	v_mov_b32_e32 v48, v16
	v_mov_b32_e32 v49, v16
	v_mov_b32_e32 v50, v16
	v_mov_b32_e32 v51, v16
	v_mov_b32_e32 v52, v16
	v_mov_b32_e32 v53, v16
	v_mov_b32_e32 v54, v16
	v_mov_b32_e32 v55, v16
	v_mov_b32_e32 v56, v16
	v_mov_b32_e32 v57, v16
	v_mov_b32_e32 v58, v16
	v_mov_b32_e32 v59, v16
	v_mov_b32_e32 v60, v16
	v_mov_b32_e32 v61, v16
	v_mov_b32_e32 v62, v16
	v_mov_b32_e32 v63, v16
	s_branch .LBB0_511
; __device__ __forceinline__ void phase_hyena(int l, LAS unsigned char* lds, int G) {
;     ...
;         { int D = Dlo;
;           for (; D < 8 * wave - 59; ++D) HY_BODY(true, false);
.LBB0_510:
	s_setprio 1
	s_waitcnt lgkmcnt(0)
	v_mfma_f32_32x32x16_bf16 v[48:63], v[32:35], v[44:47], v[48:63]
	v_mfma_f32_32x32x16_bf16 v[16:31], v[6:9], v[44:47], v[16:31]
	v_mfma_f32_32x32x16_bf16 v[48:63], v[10:13], v[68:71], v[48:63]
	v_mfma_f32_32x32x16_bf16 v[16:31], v[2:5], v[68:71], v[16:31]
	v_mfma_f32_32x32x16_bf16 v[48:63], v[40:43], v[64:67], v[48:63]
	v_mfma_f32_32x32x16_bf16 v[16:31], v[32:35], v[64:67], v[16:31]
	v_mfma_f32_32x32x16_bf16 v[48:63], v[36:39], v[72:75], v[48:63]
	v_mfma_f32_32x32x16_bf16 v[16:31], v[10:13], v[72:75], v[16:31]
	s_setprio 0
	s_add_i32 s2, s2, 1
	v_add_u32_e32 v15, 0xffffff80, v15
	v_add_u32_e32 v14, -1, v14
	s_cmp_ge_i32 s2, s77
	v_add_u32_e32 v0, 0xffffff80, v0
	s_cbranch_scc1 .LBB0_532
.LBB0_511:
	v_add_u32_e32 v36, v15, v128
	v_add_u32_e32 v2, 0x12040, v36
	v_add_u32_e32 v3, 0x12048, v36
	v_add_u32_e32 v4, 0x12060, v36
	v_add_u32_e32 v5, 0x12068, v36
	v_add_u32_e32 v10, 0x12080, v36
	v_add_u32_e32 v11, 0x12088, v36
	v_add_u32_e32 v12, 0x120a0, v36
	v_add_u32_e32 v13, 0x120a8, v36
	v_add_u32_e32 v37, 0x120c0, v36
	v_add_u32_e32 v38, 0x120c8, v36
	v_add_u32_e32 v39, 0x120e0, v36
	ds_read2_b32 v[6:7], v2 offset1:1
	ds_read2_b32 v[8:9], v3 offset1:1
	ds_read2_b32 v[2:3], v4 offset1:1
	ds_read2_b32 v[4:5], v5 offset1:1
	ds_read2_b32 v[32:33], v10 offset1:1
	ds_read2_b32 v[34:35], v11 offset1:1
	ds_read2_b32 v[10:11], v12 offset1:1
	ds_read2_b32 v[12:13], v13 offset1:1
	v_add_u32_e32 v44, 0x120e8, v36
	ds_read2_b32 v[40:41], v37 offset1:1
	ds_read2_b32 v[42:43], v38 offset1:1
	ds_read2_b32 v[36:37], v39 offset1:1
	ds_read2_b32 v[38:39], v44 offset1:1
	v_cmp_gt_u32_e32 vcc, 64, v14
	v_add_u32_e32 v76, v0, v128
	s_nop 0
	v_cndmask_b32_e32 v76, v227, v76, vcc
	ds_read_b128 v[44:47], v76
	ds_read_b128 v[68:71], v76 offset:32
	ds_read_b128 v[64:67], v76 offset:64
	ds_read_b128 v[72:75], v76 offset:96
	s_branch .LBB0_510

; __device__ __forceinline__ void phase_hyena(int l, LAS unsigned char* lds, int G) {
;     ...
;           for (; D <= Dhi; ++D) HY_BODY(false, true); }
.LBB0_523:
	s_setprio 1
	s_waitcnt lgkmcnt(0)
	v_mfma_f32_32x32x16_bf16 v[64:79], v[80:83], v[96:99], v[64:79]
	v_mfma_f32_32x32x16_bf16 v[32:47], v[6:9], v[96:99], v[32:47]
	v_mfma_f32_32x32x16_bf16 v[64:79], v[10:13], v[92:95], v[64:79]
	v_mfma_f32_32x32x16_bf16 v[32:47], v[2:5], v[92:95], v[32:47]
	v_mfma_f32_32x32x16_bf16 v[64:79], v[88:91], v[104:107], v[64:79]
	v_mfma_f32_32x32x16_bf16 v[32:47], v[80:83], v[104:107], v[32:47]
	v_mfma_f32_32x32x16_bf16 v[64:79], v[84:87], v[100:103], v[64:79]
	v_mfma_f32_32x32x16_bf16 v[32:47], v[10:13], v[100:103], v[32:47]
	s_setprio 0
	s_add_i32 s2, s2, 1
	v_add_u32_e32 v0, 0xffffff80, v0
	v_add_u32_e32 v14, -1, v14
	s_cmp_ge_i32 s2, s71
	v_add_u32_e32 v15, 0xffffff80, v15
	s_cbranch_scc1 .LBB0_475
.LBB0_524:
	v_add_u32_e32 v84, v0, v128
	v_add_u32_e32 v2, 0x12040, v84
	v_add_u32_e32 v3, 0x12048, v84
	v_add_u32_e32 v4, 0x12060, v84
	v_add_u32_e32 v5, 0x12068, v84
	v_add_u32_e32 v10, 0x12080, v84
	v_add_u32_e32 v11, 0x12088, v84
	v_add_u32_e32 v12, 0x120a0, v84
	v_add_u32_e32 v13, 0x120a8, v84
	v_add_u32_e32 v85, 0x120c0, v84
	v_add_u32_e32 v86, 0x120c8, v84
	v_add_u32_e32 v87, 0x120e0, v84
	ds_read2_b32 v[6:7], v2 offset1:1
	ds_read2_b32 v[8:9], v3 offset1:1
	ds_read2_b32 v[2:3], v4 offset1:1
	ds_read2_b32 v[4:5], v5 offset1:1
	ds_read2_b32 v[80:81], v10 offset1:1
	ds_read2_b32 v[82:83], v11 offset1:1
	ds_read2_b32 v[10:11], v12 offset1:1
	ds_read2_b32 v[12:13], v13 offset1:1
	v_add_u32_e32 v92, 0x120e8, v84
	ds_read2_b32 v[88:89], v85 offset1:1
	ds_read2_b32 v[90:91], v86 offset1:1
	ds_read2_b32 v[84:85], v87 offset1:1
	ds_read2_b32 v[86:87], v92 offset1:1
	v_cmp_gt_u32_e32 vcc, 64, v14
	v_add_u32_e32 v108, v15, v128
	s_nop 0
	v_cndmask_b32_e32 v108, v227, v108, vcc
	ds_read_b128 v[96:99], v108
	ds_read_b128 v[92:95], v108 offset:32
	ds_read_b128 v[104:107], v108 offset:64
	ds_read_b128 v[100:103], v108 offset:96
	s_branch .LBB0_523

; __device__ __forceinline__ void phase_hyena(int l, LAS unsigned char* lds, int G) {
;     ...
;           for (; D <= 8 * wave + 3; ++D) HY_BODY(true, true);
.LBB0_534:
	s_setprio 1
	s_waitcnt lgkmcnt(0)
	v_mfma_f32_32x32x16_bf16 v[48:63], v[10:13], v[92:95], v[48:63]
	v_mfma_f32_32x32x16_bf16 v[64:79], v[10:13], v[108:111], v[64:79]
	v_mfma_f32_32x32x16_bf16 v[16:31], v[80:83], v[92:95], v[16:31]
	v_mfma_f32_32x32x16_bf16 v[32:47], v[80:83], v[108:111], v[32:47]
	v_mfma_f32_32x32x16_bf16 v[48:63], v[2:5], v[100:103], v[48:63]
	v_mfma_f32_32x32x16_bf16 v[64:79], v[2:5], v[116:119], v[64:79]
	v_mfma_f32_32x32x16_bf16 v[16:31], v[6:9], v[100:103], v[16:31]
	v_mfma_f32_32x32x16_bf16 v[32:47], v[6:9], v[116:119], v[32:47]
	v_mfma_f32_32x32x16_bf16 v[48:63], v[88:91], v[96:99], v[48:63]
	v_mfma_f32_32x32x16_bf16 v[64:79], v[88:91], v[112:115], v[64:79]
	v_mfma_f32_32x32x16_bf16 v[16:31], v[10:13], v[96:99], v[16:31]
	v_mfma_f32_32x32x16_bf16 v[32:47], v[10:13], v[112:115], v[32:47]
	v_mfma_f32_32x32x16_bf16 v[48:63], v[84:87], v[104:107], v[48:63]
	v_mfma_f32_32x32x16_bf16 v[64:79], v[84:87], v[120:123], v[64:79]
	v_mfma_f32_32x32x16_bf16 v[16:31], v[2:5], v[104:107], v[16:31]
	v_mfma_f32_32x32x16_bf16 v[32:47], v[2:5], v[120:123], v[32:47]
	s_setprio 0
	s_add_i32 s3, s2, 1
	v_add_u32_e32 v155, 0xffffff80, v155
	v_add_u32_e32 v15, -1, v15
	v_add_u32_e32 v14, 0xffffff80, v14
	s_cmp_ge_i32 s2, s78
	v_add_u32_e32 v0, 0xffffff80, v0
	s_mov_b32 s2, s3
	s_cbranch_scc1 .LBB0_521
.LBB0_535:
	v_add_u32_e32 v84, v155, v128
	v_add_u32_e32 v2, 0x12040, v84
	v_add_u32_e32 v3, 0x12048, v84
	v_add_u32_e32 v4, 0x12060, v84
	v_add_u32_e32 v5, 0x12068, v84
	ds_read2_b32 v[80:81], v2 offset1:1
	ds_read2_b32 v[82:83], v3 offset1:1
	ds_read2_b32 v[6:7], v4 offset1:1
	ds_read2_b32 v[8:9], v5 offset1:1
	v_add_u32_e32 v2, 0x12080, v84
	v_add_u32_e32 v3, 0x12088, v84
	v_add_u32_e32 v4, 0x120a0, v84
	v_add_u32_e32 v5, 0x120a8, v84
	v_add_u32_e32 v85, 0x120c0, v84
	v_add_u32_e32 v86, 0x120c8, v84
	v_add_u32_e32 v87, 0x120e0, v84
	ds_read2_b32 v[10:11], v2 offset1:1
	ds_read2_b32 v[12:13], v3 offset1:1
	ds_read2_b32 v[2:3], v4 offset1:1
	ds_read2_b32 v[4:5], v5 offset1:1
	v_add_u32_e32 v92, 0x120e8, v84
	ds_read2_b32 v[88:89], v85 offset1:1
	ds_read2_b32 v[90:91], v86 offset1:1
	ds_read2_b32 v[84:85], v87 offset1:1
	ds_read2_b32 v[86:87], v92 offset1:1
	v_cmp_gt_u32_e32 vcc, 64, v15
	v_add_u32_e32 v109, v14, v128
	s_nop 0
	v_cndmask_b32_e32 v109, v227, v109, vcc
	ds_read_b128 v[92:95], v109
	ds_read_b128 v[100:103], v109 offset:32
	ds_read_b128 v[96:99], v109 offset:64
	ds_read_b128 v[104:107], v109 offset:96
	v_add_u32_e32 v108, 4, v15
	v_cmp_gt_u32_e32 vcc, 64, v108
	v_add_u32_e32 v156, v0, v128
	s_nop 0
	v_cndmask_b32_e32 v156, v227, v156, vcc
	ds_read_b128 v[108:111], v156
	ds_read_b128 v[116:119], v156 offset:32
	ds_read_b128 v[112:115], v156 offset:64
	ds_read_b128 v[120:123], v156 offset:96
	s_branch .LBB0_534
